# v64 + grid barrier: the first block of an XCD to arrive also issues an early buffer_wbl2 (hint)
# baseline (speedup 1.0000x reference)
.LBB0_411:
	global_atomic_add v3, v[140:141], v166, off sc0
	v_cvt_f32_u32_e32 v1, v2
	v_sub_u32_e32 v4, 0, v2
	v_rcp_iflag_f32_e32 v1, v1
	s_nop 0
	v_mul_f32_e32 v1, 0x4f7ffffe, v1
	v_cvt_u32_f32_e32 v1, v1
	v_mul_lo_u32 v4, v4, v1
	v_mul_hi_u32 v4, v1, v4
	v_add_u32_e32 v1, v1, v4
	s_waitcnt vmcnt(0)
	v_mul_hi_u32 v1, v3, v1
	v_mul_lo_u32 v4, v1, v2
	v_sub_u32_e32 v4, v3, v4
	v_add_u32_e32 v5, 1, v1
	v_cmp_ge_u32_e32 vcc, v4, v2
	v_add_u32_e32 v3, 1, v3
	s_nop 0
	v_cndmask_b32_e32 v1, v1, v5, vcc
	v_sub_u32_e32 v5, v4, v2
	v_cndmask_b32_e32 v4, v4, v5, vcc
	v_add_u32_e32 v5, 1, v1
	v_cmp_ge_u32_e32 vcc, v4, v2
	s_nop 1
	v_cndmask_b32_e32 v1, v1, v5, vcc
	v_mul_lo_u32 v4, v2, v1
	v_add_u32_e32 v2, v4, v2
	v_cmp_ne_u32_e32 vcc, v3, v2
	s_and_saveexec_b64 s[2:3], vcc
	s_xor_b64 s[2:3], exec, s[2:3]
	s_cbranch_execz .LBB0_425
	s_waitcnt lgkmcnt(0)
	v_add_u32_e32 v4, 1, v4
	v_cmp_eq_u32_e32 vcc, v3, v4
	s_cbranch_vccz .Lewb_0
	buffer_wbl2 sc1
.Lewb_0:
	global_load_dword v0, v[142:143], off sc1
	s_waitcnt vmcnt(0)
	v_cmp_eq_u32_e32 vcc, v0, v1
	s_and_saveexec_b64 s[4:5], vcc
	s_cbranch_execz .LBB0_424
	s_mov_b32 s12, 1
	s_mov_b64 s[6:7], 0
	s_branch .LBB0_415

.LBB0_1393:
	global_atomic_add v3, v[140:141], v166, off sc0
	v_cvt_f32_u32_e32 v1, v2
	v_sub_u32_e32 v4, 0, v2
	v_rcp_iflag_f32_e32 v1, v1
	s_nop 0
	v_mul_f32_e32 v1, 0x4f7ffffe, v1
	v_cvt_u32_f32_e32 v1, v1
	v_mul_lo_u32 v4, v4, v1
	v_mul_hi_u32 v4, v1, v4
	v_add_u32_e32 v1, v1, v4
	s_waitcnt vmcnt(0)
	v_mul_hi_u32 v1, v3, v1
	v_mul_lo_u32 v4, v1, v2
	v_sub_u32_e32 v4, v3, v4
	v_add_u32_e32 v5, 1, v1
	v_cmp_ge_u32_e32 vcc, v4, v2
	v_add_u32_e32 v3, 1, v3
	s_nop 0
	v_cndmask_b32_e32 v1, v1, v5, vcc
	v_sub_u32_e32 v5, v4, v2
	v_cndmask_b32_e32 v4, v4, v5, vcc
	v_add_u32_e32 v5, 1, v1
	v_cmp_ge_u32_e32 vcc, v4, v2
	s_nop 1
	v_cndmask_b32_e32 v1, v1, v5, vcc
	v_mul_lo_u32 v4, v2, v1
	v_add_u32_e32 v2, v4, v2
	v_cmp_ne_u32_e32 vcc, v3, v2
	s_and_saveexec_b64 s[4:5], vcc
	s_xor_b64 s[4:5], exec, s[4:5]
	s_cbranch_execz .LBB0_1407
	s_waitcnt lgkmcnt(0)
	v_add_u32_e32 v4, 1, v4
	v_cmp_eq_u32_e32 vcc, v3, v4
	s_cbranch_vccz .Lewb_7
	buffer_wbl2 sc1
.Lewb_7:
	global_load_dword v0, v[142:143], off sc1
	s_waitcnt vmcnt(0)
	v_cmp_eq_u32_e32 vcc, v0, v1
	s_and_saveexec_b64 s[6:7], vcc
	s_cbranch_execz .LBB0_1406
	s_mov_b32 s1, 1
	s_mov_b64 s[8:9], 0
	s_branch .LBB0_1397
